# filter-generation loop of hyena stage 0: a3 loads software-pipelined 3 deep (global_load, counted vmcnt)
# speedup vs baseline: 1.2449x; 1.0128x over previous
; __device__ __forceinline__ void phase_hyena(KP kp_, int hf){ asm volatile("" : "+s"(kp_)); const Params p=load_params(kp_);
;     ...
;       int n=lane&15, kg=lane>>4;
;       f16x8 bw0, bw1;
;       _Pragma("unroll") for (int e=0;e<8;++e){ bw0[e]=(n<4)?(_Float16)misc[(kg*8+e)*4+n]:(_Float16)0.f; bw1[e]=(n<4)?(_Float16)misc[(32+kg*8+e)*4+n]:(_Float16)0.f; }
;       const float dsc=-delta*(1.f/8191.f);
;       float pj0=__expf(dsc*(float)(kg*4)), pj1=__expf(dsc*(float)(kg*4+1)), pj2=__expf(dsc*(float)(kg*4+2)), pj3=__expf(dsc*(float)(kg*4+3));
;       float* Zf=(float*)Z; float ssl=0.f; int order=n&1; bool side1=(n&2)!=0;
;       _Pragma("unroll 8") for (int i=0;i<64;++i){ int tl=wid+8*i;
;         const _Float16* ap=a3+(size_t)(tl*16+n)*64+kg*8;
;         f16x8 a0=*(const f16x8*)ap, a1=*(const f16x8*)(ap+32);
.LBB0_1232:
	s_or_b64 exec, exec, s[12:13]
	v_perm_b32 v3, v15, v3, s82
	v_perm_b32 v2, v7, v2, s82
	v_perm_b32 v1, v6, v1, s82
	v_perm_b32 v0, v5, v0, s82
	v_perm_b32 v7, v14, v13, s82
	v_perm_b32 v6, v12, v11, s82
	v_perm_b32 v5, v10, v9, s82
	v_perm_b32 v4, v8, v4, s82
	v_mov_b32_e32 v28, 0
	s_mov_b32 s18, 0
	v_mov_b32_e32 v29, v216
	v_mov_b64_e32 v[12:13], v[72:73]
	v_mov_b64_e32 v[14:15], v[70:71]
	v_mov_b64_e32 v[16:17], v[68:69]
	v_mov_b64_e32 v[18:19], v[66:67]
	v_mov_b64_e32 v[20:21], v[64:65]
	v_mov_b64_e32 v[22:23], v[62:63]
	v_mov_b64_e32 v[24:25], v[60:61]
	v_mov_b64_e32 v[26:27], v[58:59]
	v_mov_b32_e32 v30, v214
	v_mov_b32_e32 v31, v213
	v_mov_b32_e32 v78, v212
	s_mov_b32 s19, 0
	v_lshl_add_u64 v[84:85], v[18:19], 0, v[132:133]
	v_add_co_u32_e32 v84, vcc, 0x3b89000, v84
	s_nop 1
	v_addc_co_u32_e32 v85, vcc, 0, v85, vcc
	global_load_dwordx4 v[228:231], v[84:85], off
	global_load_dwordx4 v[232:235], v[84:85], off offset:64
	v_lshl_add_u64 v[84:85], v[12:13], 0, v[132:133]
	v_add_co_u32_e32 v84, vcc, 0x3b89000, v84
	s_nop 1
	v_addc_co_u32_e32 v85, vcc, 0, v85, vcc
	global_load_dwordx4 v[236:239], v[84:85], off
	global_load_dwordx4 v[240:243], v[84:85], off offset:64
	v_lshl_add_u64 v[84:85], v[14:15], 0, v[132:133]
	v_add_co_u32_e32 v84, vcc, 0x3b89000, v84
	s_nop 1
	v_addc_co_u32_e32 v85, vcc, 0, v85, vcc
	global_load_dwordx4 v[244:247], v[84:85], off
	global_load_dwordx4 v[248:251], v[84:85], off offset:64
	s_branch .LBB0_1235

; __device__ __forceinline__ void phase_hyena(KP kp_, int hf){ asm volatile("" : "+s"(kp_)); const Params p=load_params(kp_);
;     ...
;       _Pragma("unroll 8") for (int i=0;i<64;++i){ int tl=wid+8*i;
;         const _Float16* ap=a3+(size_t)(tl*16+n)*64+kg*8;
;         f16x8 a0=*(const f16x8*)ap, a1=*(const f16x8*)(ap+32);
;         f32x4 dd={0.f,0.f,0.f,0.f};
;         dd=__builtin_amdgcn_mfma_f32_16x16x32_f16(a0,bw0,dd,0,0,0);
;         dd=__builtin_amdgcn_mfma_f32_16x16x32_f16(a1,bw1,dd,0,0,0);
;         if (n<4){ float d0=__expf(dsc*(float)(tl*16)); int lag0=tl*16+kg*4;
;           float v0=dd[0]*d0*pj0, v1=dd[1]*d0*pj1, v2=dd[2]*d0*pj2, v3=dd[3]*d0*pj3;
;           if (!side1){ Zf[2*(lag0)+order]=v0; Zf[2*(lag0+1)+order]=v1; Zf[2*(lag0+2)+order]=v2; Zf[2*(lag0+3)+order]=v3; ssl+=v0*v0+v1*v1+v2*v2+v3*v3; }
;           else { if (lag0>=1){ Zf[2*(16384-lag0)+order]=v0; ssl+=v0*v0; }
;             Zf[2*(16384-lag0-1)+order]=v1; Zf[2*(16384-lag0-2)+order]=v2; Zf[2*(16384-lag0-3)+order]=v3; ssl+=v1*v1+v2*v2+v3*v3; } }
.LBB0_1235:
	s_lshl_b32 s22, s19, 7
	s_nop 0
	s_nop 0
	v_add_u32_e32 v79, s18, v98
	s_waitcnt vmcnt(2)
	v_mfma_f32_16x16x32_f16 v[8:11], v[228:231], v[0:3], 0
	v_mfma_f32_16x16x32_f16 v[8:11], v[232:235], v[4:7], v[8:11]
	v_lshl_add_u64 v[84:85], v[16:17], 0, v[132:133]
	v_add_co_u32_e32 v84, vcc, 0x3b89000, v84
	s_nop 1
	v_addc_co_u32_e32 v85, vcc, 0, v85, vcc
	global_load_dwordx4 v[228:231], v[84:85], off
	global_load_dwordx4 v[232:235], v[84:85], off offset:64
	s_and_saveexec_b64 s[50:51], s[38:39]
	s_cbranch_execz .LBB0_1245
	v_cvt_f32_i32_e32 v80, v79
	v_mul_f32_e32 v80, v93, v80
	v_mul_f32_e32 v80, 0x3fb8aa3b, v80
	v_exp_f32_e32 v82, v80
	s_nop 1
	v_mul_f32_e32 v80, v8, v82
	v_mov_b32_e32 v8, v11
	v_mul_f32_e32 v81, v10, v82
	v_pk_mul_f32 v[8:9], v[8:9], v[82:83] op_sel_hi:[1,0]
	v_mul_f32_e32 v10, v95, v80
	v_mul_f32_e32 v80, v96, v81
	v_pk_mul_f32 v[8:9], v[50:51], v[8:9]
	s_and_saveexec_b64 s[12:13], s[40:41]
	s_xor_b64 s[12:13], exec, s[12:13]
	s_cbranch_execz .LBB0_1242
	v_add_u32_e32 v11, s18, v215
	v_cmp_gt_i32_e32 vcc, 1, v11
	s_and_saveexec_b64 s[26:27], vcc
	s_xor_b64 vcc, exec, s[26:27]
	v_add_u32_e32 v11, 0x700, v31
	s_andn2_saveexec_b64 vcc, vcc
	s_cbranch_execz .LBB0_1241
	v_add_u32_e32 v11, s22, v98
	v_or_b32_e32 v11, v11, v94
	v_lshlrev_b32_e32 v11, 1, v11
	v_fmac_f32_e32 v28, v10, v10
	v_sub_u32_e32 v11, v97, v11
	v_add_u32_e32 v81, 0, v29
	ds_write_b32 v81, v10

; __device__ __forceinline__ void phase_hyena(KP kp_, int hf){ asm volatile("" : "+s"(kp_)); const Params p=load_params(kp_);
;     ...
;       _Pragma("unroll 8") for (int i=0;i<64;++i){ int tl=wid+8*i;
;         const _Float16* ap=a3+(size_t)(tl*16+n)*64+kg*8;
;         f16x8 a0=*(const f16x8*)ap, a1=*(const f16x8*)(ap+32);
;         f32x4 dd={0.f,0.f,0.f,0.f};
;         dd=__builtin_amdgcn_mfma_f32_16x16x32_f16(a0,bw0,dd,0,0,0);
;         dd=__builtin_amdgcn_mfma_f32_16x16x32_f16(a1,bw1,dd,0,0,0);
;         if (n<4){ float d0=__expf(dsc*(float)(tl*16)); int lag0=tl*16+kg*4;
;           float v0=dd[0]*d0*pj0, v1=dd[1]*d0*pj1, v2=dd[2]*d0*pj2, v3=dd[3]*d0*pj3;
;           if (!side1){ Zf[2*(lag0)+order]=v0; Zf[2*(lag0+1)+order]=v1; Zf[2*(lag0+2)+order]=v2; Zf[2*(lag0+3)+order]=v3; ssl+=v0*v0+v1*v1+v2*v2+v3*v3; }
;           else { if (lag0>=1){ Zf[2*(16384-lag0)+order]=v0; ssl+=v0*v0; }
;             Zf[2*(16384-lag0-1)+order]=v1; Zf[2*(16384-lag0-2)+order]=v2; Zf[2*(16384-lag0-3)+order]=v3; ssl+=v1*v1+v2*v2+v3*v3; } }
.LBB0_1245:
	s_or_b64 exec, exec, s[50:51]
	s_nop 4
	s_nop 1
	s_nop 0
	s_waitcnt vmcnt(2)
	v_mfma_f32_16x16x32_f16 v[8:11], v[236:239], v[0:3], 0
	v_mfma_f32_16x16x32_f16 v[8:11], v[240:243], v[4:7], v[8:11]
	v_lshl_add_u64 v[84:85], v[20:21], 0, v[132:133]
	v_add_co_u32_e32 v84, vcc, 0x3b89000, v84
	s_nop 1
	v_addc_co_u32_e32 v85, vcc, 0, v85, vcc
	global_load_dwordx4 v[236:239], v[84:85], off
	global_load_dwordx4 v[240:243], v[84:85], off offset:64
	s_and_saveexec_b64 s[50:51], s[38:39]
	s_cbranch_execz .LBB0_1255
	v_add_u32_e32 v80, 0x80, v79
	v_cvt_f32_i32_e32 v80, v80
	v_mul_f32_e32 v80, v93, v80
	v_mul_f32_e32 v80, 0x3fb8aa3b, v80
	v_exp_f32_e32 v82, v80
	s_nop 0
	v_mul_f32_e32 v80, v8, v82
	v_mov_b32_e32 v8, v11
	v_mul_f32_e32 v81, v10, v82
	v_pk_mul_f32 v[8:9], v[8:9], v[82:83] op_sel_hi:[1,0]
	v_mul_f32_e32 v10, v95, v80
	v_mul_f32_e32 v80, v96, v81
	v_pk_mul_f32 v[8:9], v[50:51], v[8:9]
	s_and_saveexec_b64 s[12:13], s[40:41]
	s_xor_b64 s[12:13], exec, s[12:13]
	s_cbranch_execz .LBB0_1252
	v_add_u32_e32 v11, s18, v215
	v_add_u32_e32 v11, 0x80, v11
	v_cmp_gt_i32_e32 vcc, 1, v11
	s_and_saveexec_b64 s[26:27], vcc
	s_xor_b64 vcc, exec, s[26:27]
	v_add_u32_e32 v10, s22, v98
	v_add_lshl_u32 v10, v10, v94, 1
	v_sub_u32_e32 v10, v97, v10
	v_add_u32_e32 v11, 0xffffff00, v10
	s_andn2_saveexec_b64 vcc, vcc
	v_add_u32_e32 v81, 0, v30
	v_fmac_f32_e32 v28, v10, v10
	v_add_u32_e32 v11, 0x600, v31
	v_add_u32_e32 v81, 0x1fc00, v81
	ds_write_b32 v81, v10
	s_or_b64 exec, exec, vcc
	v_lshl_add_u32 v10, v11, 2, 0
	v_add_u32_e32 v11, 0x1fff8, v10
	ds_write_b32 v11, v9
	v_add_u32_e32 v11, 0x1fff0, v10
	v_add_u32_e32 v10, 0x1ffe8, v10
	ds_write_b32 v10, v8
	v_pk_mul_f32 v[8:9], v[8:9], v[8:9]
	ds_write_b32 v11, v80
	v_fma_f32 v9, v80, v80, v9
	v_add_f32_e32 v8, v8, v9
	v_add_f32_e32 v28, v8, v28

; __device__ __forceinline__ void phase_hyena(KP kp_, int hf){ asm volatile("" : "+s"(kp_)); const Params p=load_params(kp_);
;     ...
;       _Pragma("unroll 8") for (int i=0;i<64;++i){ int tl=wid+8*i;
;         const _Float16* ap=a3+(size_t)(tl*16+n)*64+kg*8;
;         f16x8 a0=*(const f16x8*)ap, a1=*(const f16x8*)(ap+32);
;         f32x4 dd={0.f,0.f,0.f,0.f};
;         dd=__builtin_amdgcn_mfma_f32_16x16x32_f16(a0,bw0,dd,0,0,0);
;         dd=__builtin_amdgcn_mfma_f32_16x16x32_f16(a1,bw1,dd,0,0,0);
;         if (n<4){ float d0=__expf(dsc*(float)(tl*16)); int lag0=tl*16+kg*4;
;           float v0=dd[0]*d0*pj0, v1=dd[1]*d0*pj1, v2=dd[2]*d0*pj2, v3=dd[3]*d0*pj3;
;           if (!side1){ Zf[2*(lag0)+order]=v0; Zf[2*(lag0+1)+order]=v1; Zf[2*(lag0+2)+order]=v2; Zf[2*(lag0+3)+order]=v3; ssl+=v0*v0+v1*v1+v2*v2+v3*v3; }
;           else { if (lag0>=1){ Zf[2*(16384-lag0)+order]=v0; ssl+=v0*v0; }
;             Zf[2*(16384-lag0-1)+order]=v1; Zf[2*(16384-lag0-2)+order]=v2; Zf[2*(16384-lag0-3)+order]=v3; ssl+=v1*v1+v2*v2+v3*v3; } }
.LBB0_1255:
	s_or_b64 exec, exec, s[50:51]
	s_nop 4
	s_nop 1
	s_nop 0
	s_waitcnt vmcnt(4)
	v_mfma_f32_16x16x32_f16 v[8:11], v[244:247], v[0:3], 0
	v_mfma_f32_16x16x32_f16 v[8:11], v[248:251], v[4:7], v[8:11]
	v_lshl_add_u64 v[84:85], v[22:23], 0, v[132:133]
	v_add_co_u32_e32 v84, vcc, 0x3b89000, v84
	s_nop 1
	v_addc_co_u32_e32 v85, vcc, 0, v85, vcc
	global_load_dwordx4 v[244:247], v[84:85], off
	global_load_dwordx4 v[248:251], v[84:85], off offset:64
	s_and_saveexec_b64 s[50:51], s[38:39]
	s_cbranch_execz .LBB0_1265
	v_add_u32_e32 v80, 0x100, v79
	v_cvt_f32_i32_e32 v80, v80
	v_mul_f32_e32 v80, v93, v80
	v_mul_f32_e32 v80, 0x3fb8aa3b, v80
	v_exp_f32_e32 v82, v80
	s_nop 0
	v_mul_f32_e32 v80, v8, v82
	v_mov_b32_e32 v8, v11
	v_mul_f32_e32 v81, v10, v82
	v_pk_mul_f32 v[8:9], v[8:9], v[82:83] op_sel_hi:[1,0]
	v_mul_f32_e32 v10, v95, v80
	v_mul_f32_e32 v80, v96, v81
	v_pk_mul_f32 v[8:9], v[50:51], v[8:9]
	s_and_saveexec_b64 s[12:13], s[40:41]
	s_xor_b64 s[12:13], exec, s[12:13]
	s_cbranch_execz .LBB0_1262
	v_add_u32_e32 v11, s18, v215
	v_add_u32_e32 v11, 0x100, v11
	v_cmp_gt_i32_e32 vcc, 1, v11
	s_and_saveexec_b64 s[26:27], vcc
	s_xor_b64 vcc, exec, s[26:27]
	v_add_u32_e32 v10, s22, v98
	v_add_lshl_u32 v10, v10, v94, 1
	v_sub_u32_e32 v10, v97, v10
	v_add_u32_e32 v11, 0xfffffe00, v10
	s_andn2_saveexec_b64 vcc, vcc
	v_add_u32_e32 v81, 0, v30
	v_fmac_f32_e32 v28, v10, v10
	v_add_u32_e32 v11, 0x500, v31
	v_add_u32_e32 v81, 0x1f800, v81
	ds_write_b32 v81, v10
	s_or_b64 exec, exec, vcc
	v_lshl_add_u32 v10, v11, 2, 0
	v_add_u32_e32 v11, 0x1fff8, v10
	ds_write_b32 v11, v9
	v_add_u32_e32 v11, 0x1fff0, v10
	v_add_u32_e32 v10, 0x1ffe8, v10
	ds_write_b32 v10, v8
	v_pk_mul_f32 v[8:9], v[8:9], v[8:9]
	ds_write_b32 v11, v80
	v_fma_f32 v9, v80, v80, v9
	v_add_f32_e32 v8, v8, v9
	v_add_f32_e32 v28, v8, v28

; __device__ __forceinline__ void phase_hyena(KP kp_, int hf){ asm volatile("" : "+s"(kp_)); const Params p=load_params(kp_);
;     ...
;       _Pragma("unroll 8") for (int i=0;i<64;++i){ int tl=wid+8*i;
;         const _Float16* ap=a3+(size_t)(tl*16+n)*64+kg*8;
;         f16x8 a0=*(const f16x8*)ap, a1=*(const f16x8*)(ap+32);
;         f32x4 dd={0.f,0.f,0.f,0.f};
;         dd=__builtin_amdgcn_mfma_f32_16x16x32_f16(a0,bw0,dd,0,0,0);
;         dd=__builtin_amdgcn_mfma_f32_16x16x32_f16(a1,bw1,dd,0,0,0);
;         if (n<4){ float d0=__expf(dsc*(float)(tl*16)); int lag0=tl*16+kg*4;
;           float v0=dd[0]*d0*pj0, v1=dd[1]*d0*pj1, v2=dd[2]*d0*pj2, v3=dd[3]*d0*pj3;
;           if (!side1){ Zf[2*(lag0)+order]=v0; Zf[2*(lag0+1)+order]=v1; Zf[2*(lag0+2)+order]=v2; Zf[2*(lag0+3)+order]=v3; ssl+=v0*v0+v1*v1+v2*v2+v3*v3; }
;           else { if (lag0>=1){ Zf[2*(16384-lag0)+order]=v0; ssl+=v0*v0; }
;             Zf[2*(16384-lag0-1)+order]=v1; Zf[2*(16384-lag0-2)+order]=v2; Zf[2*(16384-lag0-3)+order]=v3; ssl+=v1*v1+v2*v2+v3*v3; } }
.LBB0_1265:
	s_or_b64 exec, exec, s[50:51]
	s_nop 4
	s_nop 1
	s_nop 0
	s_waitcnt vmcnt(4)
	v_mfma_f32_16x16x32_f16 v[8:11], v[228:231], v[0:3], 0
	v_mfma_f32_16x16x32_f16 v[8:11], v[232:235], v[4:7], v[8:11]
	v_lshl_add_u64 v[84:85], v[24:25], 0, v[132:133]
	v_add_co_u32_e32 v84, vcc, 0x3b89000, v84
	s_nop 1
	v_addc_co_u32_e32 v85, vcc, 0, v85, vcc
	global_load_dwordx4 v[228:231], v[84:85], off
	global_load_dwordx4 v[232:235], v[84:85], off offset:64
	s_and_saveexec_b64 s[50:51], s[38:39]
	s_cbranch_execz .LBB0_1275
	v_add_u32_e32 v80, 0x180, v79
	v_cvt_f32_i32_e32 v80, v80
	v_mul_f32_e32 v80, v93, v80
	v_mul_f32_e32 v80, 0x3fb8aa3b, v80
	v_exp_f32_e32 v82, v80
	s_nop 0
	v_mul_f32_e32 v80, v8, v82
	v_mov_b32_e32 v8, v11
	v_mul_f32_e32 v81, v10, v82
	v_pk_mul_f32 v[8:9], v[8:9], v[82:83] op_sel_hi:[1,0]
	v_mul_f32_e32 v10, v95, v80
	v_mul_f32_e32 v80, v96, v81
	v_pk_mul_f32 v[8:9], v[50:51], v[8:9]
	s_and_saveexec_b64 s[12:13], s[40:41]
	s_xor_b64 s[12:13], exec, s[12:13]
	s_cbranch_execz .LBB0_1272
	v_add_u32_e32 v11, s18, v215
	v_add_u32_e32 v11, 0x180, v11
	v_cmp_gt_i32_e32 vcc, 1, v11
	s_and_saveexec_b64 s[26:27], vcc
	s_xor_b64 vcc, exec, s[26:27]
	v_add_u32_e32 v10, s22, v98
	v_add_lshl_u32 v10, v10, v94, 1
	v_sub_u32_e32 v10, v97, v10
	v_add_u32_e32 v11, 0xfffffd00, v10
	s_andn2_saveexec_b64 vcc, vcc
	v_add_u32_e32 v81, 0, v30
	v_fmac_f32_e32 v28, v10, v10
	v_add_u32_e32 v11, 0x400, v31
	v_add_u32_e32 v81, 0x1f400, v81
	ds_write_b32 v81, v10
	s_or_b64 exec, exec, vcc
	v_lshl_add_u32 v10, v11, 2, 0
	v_add_u32_e32 v11, 0x1fff8, v10
	ds_write_b32 v11, v9
	v_add_u32_e32 v11, 0x1fff0, v10
	v_add_u32_e32 v10, 0x1ffe8, v10
	ds_write_b32 v10, v8
	v_pk_mul_f32 v[8:9], v[8:9], v[8:9]
	ds_write_b32 v11, v80
	v_fma_f32 v9, v80, v80, v9
	v_add_f32_e32 v8, v8, v9
	v_add_f32_e32 v28, v8, v28

; __device__ __forceinline__ void phase_hyena(KP kp_, int hf){ asm volatile("" : "+s"(kp_)); const Params p=load_params(kp_);
;     ...
;       _Pragma("unroll 8") for (int i=0;i<64;++i){ int tl=wid+8*i;
;         const _Float16* ap=a3+(size_t)(tl*16+n)*64+kg*8;
;         f16x8 a0=*(const f16x8*)ap, a1=*(const f16x8*)(ap+32);
;         f32x4 dd={0.f,0.f,0.f,0.f};
;         dd=__builtin_amdgcn_mfma_f32_16x16x32_f16(a0,bw0,dd,0,0,0);
;         dd=__builtin_amdgcn_mfma_f32_16x16x32_f16(a1,bw1,dd,0,0,0);
;         if (n<4){ float d0=__expf(dsc*(float)(tl*16)); int lag0=tl*16+kg*4;
;           float v0=dd[0]*d0*pj0, v1=dd[1]*d0*pj1, v2=dd[2]*d0*pj2, v3=dd[3]*d0*pj3;
;           if (!side1){ Zf[2*(lag0)+order]=v0; Zf[2*(lag0+1)+order]=v1; Zf[2*(lag0+2)+order]=v2; Zf[2*(lag0+3)+order]=v3; ssl+=v0*v0+v1*v1+v2*v2+v3*v3; }
;           else { if (lag0>=1){ Zf[2*(16384-lag0)+order]=v0; ssl+=v0*v0; }
;             Zf[2*(16384-lag0-1)+order]=v1; Zf[2*(16384-lag0-2)+order]=v2; Zf[2*(16384-lag0-3)+order]=v3; ssl+=v1*v1+v2*v2+v3*v3; } }
.LBB0_1275:
	s_or_b64 exec, exec, s[50:51]
	s_nop 4
	s_nop 1
	s_nop 0
	s_waitcnt vmcnt(4)
	v_mfma_f32_16x16x32_f16 v[8:11], v[236:239], v[0:3], 0
	v_mfma_f32_16x16x32_f16 v[8:11], v[240:243], v[4:7], v[8:11]
	v_lshl_add_u64 v[84:85], v[26:27], 0, v[132:133]
	v_add_co_u32_e32 v84, vcc, 0x3b89000, v84
	s_nop 1
	v_addc_co_u32_e32 v85, vcc, 0, v85, vcc
	global_load_dwordx4 v[236:239], v[84:85], off
	global_load_dwordx4 v[240:243], v[84:85], off offset:64
	s_and_saveexec_b64 s[50:51], s[38:39]
	s_cbranch_execz .LBB0_1285
	v_add_u32_e32 v80, 0x200, v79
	v_cvt_f32_i32_e32 v80, v80
	v_mul_f32_e32 v80, v93, v80
	v_mul_f32_e32 v80, 0x3fb8aa3b, v80
	v_exp_f32_e32 v82, v80
	s_nop 0
	v_mul_f32_e32 v80, v8, v82
	v_mov_b32_e32 v8, v11
	v_mul_f32_e32 v81, v10, v82
	v_pk_mul_f32 v[8:9], v[8:9], v[82:83] op_sel_hi:[1,0]
	v_mul_f32_e32 v10, v95, v80
	v_mul_f32_e32 v80, v96, v81
	v_pk_mul_f32 v[8:9], v[50:51], v[8:9]
	s_and_saveexec_b64 s[12:13], s[40:41]
	s_xor_b64 s[12:13], exec, s[12:13]
	s_cbranch_execz .LBB0_1282
	v_add_u32_e32 v11, s18, v215
	v_add_u32_e32 v11, 0x200, v11
	v_cmp_gt_i32_e32 vcc, 1, v11
	s_and_saveexec_b64 s[26:27], vcc
	s_xor_b64 vcc, exec, s[26:27]
	v_add_u32_e32 v10, s22, v98
	v_add_lshl_u32 v10, v10, v94, 1
	v_sub_u32_e32 v10, v97, v10
	v_add_u32_e32 v11, 0xfffffc00, v10
	s_andn2_saveexec_b64 vcc, vcc
	v_add_u32_e32 v81, 0, v30
	v_fmac_f32_e32 v28, v10, v10
	v_add_u32_e32 v11, 0x300, v31
	v_add_u32_e32 v81, 0x1f000, v81
	ds_write_b32 v81, v10
	s_or_b64 exec, exec, vcc
	v_lshl_add_u32 v10, v11, 2, 0
	v_add_u32_e32 v11, 0x1fff8, v10
	ds_write_b32 v11, v9
	v_add_u32_e32 v11, 0x1fff0, v10
	v_add_u32_e32 v10, 0x1ffe8, v10
	ds_write_b32 v10, v8
	v_pk_mul_f32 v[8:9], v[8:9], v[8:9]
	ds_write_b32 v11, v80
	v_fma_f32 v9, v80, v80, v9
	v_add_f32_e32 v8, v8, v9
	v_add_f32_e32 v28, v8, v28

; __device__ __forceinline__ void phase_hyena(KP kp_, int hf){ asm volatile("" : "+s"(kp_)); const Params p=load_params(kp_);
;     ...
;       _Pragma("unroll 8") for (int i=0;i<64;++i){ int tl=wid+8*i;
;         const _Float16* ap=a3+(size_t)(tl*16+n)*64+kg*8;
;         f16x8 a0=*(const f16x8*)ap, a1=*(const f16x8*)(ap+32);
;         f32x4 dd={0.f,0.f,0.f,0.f};
;         dd=__builtin_amdgcn_mfma_f32_16x16x32_f16(a0,bw0,dd,0,0,0);
;         dd=__builtin_amdgcn_mfma_f32_16x16x32_f16(a1,bw1,dd,0,0,0);
;         if (n<4){ float d0=__expf(dsc*(float)(tl*16)); int lag0=tl*16+kg*4;
;           float v0=dd[0]*d0*pj0, v1=dd[1]*d0*pj1, v2=dd[2]*d0*pj2, v3=dd[3]*d0*pj3;
;           if (!side1){ Zf[2*(lag0)+order]=v0; Zf[2*(lag0+1)+order]=v1; Zf[2*(lag0+2)+order]=v2; Zf[2*(lag0+3)+order]=v3; ssl+=v0*v0+v1*v1+v2*v2+v3*v3; }
;           else { if (lag0>=1){ Zf[2*(16384-lag0)+order]=v0; ssl+=v0*v0; }
;             Zf[2*(16384-lag0-1)+order]=v1; Zf[2*(16384-lag0-2)+order]=v2; Zf[2*(16384-lag0-3)+order]=v3; ssl+=v1*v1+v2*v2+v3*v3; } }
.LBB0_1285:
	s_or_b64 exec, exec, s[50:51]
	s_nop 4
	s_nop 1
	s_nop 0
	s_waitcnt vmcnt(4)
	v_mfma_f32_16x16x32_f16 v[8:11], v[244:247], v[0:3], 0
	v_mfma_f32_16x16x32_f16 v[8:11], v[248:251], v[4:7], v[8:11]
	v_lshl_add_u64 v[84:85], v[14:15], 0, v[132:133]
	v_lshl_add_u64 v[84:85], v[84:85], 0, s[0:1]
	v_add_co_u32_e32 v84, vcc, 0x3b89000, v84
	s_nop 1
	v_addc_co_u32_e32 v85, vcc, 0, v85, vcc
	global_load_dwordx4 v[244:247], v[84:85], off
	global_load_dwordx4 v[248:251], v[84:85], off offset:64
	s_and_saveexec_b64 s[50:51], s[38:39]
	s_cbranch_execz .LBB0_1295
	v_add_u32_e32 v80, 0x280, v79
	v_cvt_f32_i32_e32 v80, v80
	v_mul_f32_e32 v80, v93, v80
	v_mul_f32_e32 v80, 0x3fb8aa3b, v80
	v_exp_f32_e32 v82, v80
	s_nop 0
	v_mul_f32_e32 v80, v8, v82
	v_mov_b32_e32 v8, v11
	v_mul_f32_e32 v81, v10, v82
	v_pk_mul_f32 v[8:9], v[8:9], v[82:83] op_sel_hi:[1,0]
	v_mul_f32_e32 v10, v95, v80
	v_mul_f32_e32 v80, v96, v81
	v_pk_mul_f32 v[8:9], v[50:51], v[8:9]
	s_and_saveexec_b64 s[12:13], s[40:41]
	s_xor_b64 s[12:13], exec, s[12:13]
	s_cbranch_execz .LBB0_1292
	v_add_u32_e32 v11, s18, v215
	v_add_u32_e32 v11, 0x280, v11
	v_cmp_gt_i32_e32 vcc, 1, v11
	s_and_saveexec_b64 s[26:27], vcc
	s_xor_b64 vcc, exec, s[26:27]
	v_add_u32_e32 v10, s22, v98
	v_add_lshl_u32 v10, v10, v94, 1
	v_sub_u32_e32 v10, v97, v10
	v_add_u32_e32 v11, 0xfffffb00, v10
	s_andn2_saveexec_b64 vcc, vcc
	v_add_u32_e32 v81, 0, v30
	v_fmac_f32_e32 v28, v10, v10
	v_add_u32_e32 v11, 0x200, v31
	v_add_u32_e32 v81, 0x1ec00, v81
	ds_write_b32 v81, v10
	s_or_b64 exec, exec, vcc
	v_lshl_add_u32 v10, v11, 2, 0
	v_add_u32_e32 v11, 0x1fff8, v10
	ds_write_b32 v11, v9
	v_add_u32_e32 v11, 0x1fff0, v10
	v_add_u32_e32 v10, 0x1ffe8, v10
	ds_write_b32 v10, v8
	v_pk_mul_f32 v[8:9], v[8:9], v[8:9]
	ds_write_b32 v11, v80
	v_fma_f32 v9, v80, v80, v9
	v_add_f32_e32 v8, v8, v9
	v_add_f32_e32 v28, v8, v28

; __device__ __forceinline__ void phase_hyena(KP kp_, int hf){ asm volatile("" : "+s"(kp_)); const Params p=load_params(kp_);
;     ...
;       _Pragma("unroll 8") for (int i=0;i<64;++i){ int tl=wid+8*i;
;         const _Float16* ap=a3+(size_t)(tl*16+n)*64+kg*8;
;         f16x8 a0=*(const f16x8*)ap, a1=*(const f16x8*)(ap+32);
;         f32x4 dd={0.f,0.f,0.f,0.f};
;         dd=__builtin_amdgcn_mfma_f32_16x16x32_f16(a0,bw0,dd,0,0,0);
;         dd=__builtin_amdgcn_mfma_f32_16x16x32_f16(a1,bw1,dd,0,0,0);
;         if (n<4){ float d0=__expf(dsc*(float)(tl*16)); int lag0=tl*16+kg*4;
;           float v0=dd[0]*d0*pj0, v1=dd[1]*d0*pj1, v2=dd[2]*d0*pj2, v3=dd[3]*d0*pj3;
;           if (!side1){ Zf[2*(lag0)+order]=v0; Zf[2*(lag0+1)+order]=v1; Zf[2*(lag0+2)+order]=v2; Zf[2*(lag0+3)+order]=v3; ssl+=v0*v0+v1*v1+v2*v2+v3*v3; }
;           else { if (lag0>=1){ Zf[2*(16384-lag0)+order]=v0; ssl+=v0*v0; }
;             Zf[2*(16384-lag0-1)+order]=v1; Zf[2*(16384-lag0-2)+order]=v2; Zf[2*(16384-lag0-3)+order]=v3; ssl+=v1*v1+v2*v2+v3*v3; } }
.LBB0_1295:
	s_or_b64 exec, exec, s[50:51]
	s_nop 4
	s_nop 1
	s_nop 0
	s_waitcnt vmcnt(4)
	v_mfma_f32_16x16x32_f16 v[8:11], v[228:231], v[0:3], 0
	v_mfma_f32_16x16x32_f16 v[8:11], v[232:235], v[4:7], v[8:11]
	v_lshl_add_u64 v[84:85], v[18:19], 0, v[132:133]
	v_lshl_add_u64 v[84:85], v[84:85], 0, s[0:1]
	v_add_co_u32_e32 v84, vcc, 0x3b89000, v84
	s_nop 1
	v_addc_co_u32_e32 v85, vcc, 0, v85, vcc
	global_load_dwordx4 v[228:231], v[84:85], off
	global_load_dwordx4 v[232:235], v[84:85], off offset:64
	s_and_saveexec_b64 s[50:51], s[38:39]
	s_cbranch_execz .LBB0_1305
	v_add_u32_e32 v80, 0x300, v79
	v_cvt_f32_i32_e32 v80, v80
	v_mul_f32_e32 v80, v93, v80
	v_mul_f32_e32 v80, 0x3fb8aa3b, v80
	v_exp_f32_e32 v82, v80
	s_nop 0
	v_mul_f32_e32 v80, v8, v82
	v_mov_b32_e32 v8, v11
	v_mul_f32_e32 v81, v10, v82
	v_pk_mul_f32 v[8:9], v[8:9], v[82:83] op_sel_hi:[1,0]
	v_mul_f32_e32 v10, v95, v80
	v_mul_f32_e32 v80, v96, v81
	v_pk_mul_f32 v[8:9], v[50:51], v[8:9]
	s_and_saveexec_b64 s[12:13], s[40:41]
	s_xor_b64 s[12:13], exec, s[12:13]
	s_cbranch_execz .LBB0_1302
	v_add_u32_e32 v11, s18, v215
	v_add_u32_e32 v11, 0x300, v11
	v_cmp_gt_i32_e32 vcc, 1, v11
	s_and_saveexec_b64 s[26:27], vcc
	s_xor_b64 vcc, exec, s[26:27]
	v_add_u32_e32 v10, s22, v98
	v_add_lshl_u32 v10, v10, v94, 1
	v_sub_u32_e32 v10, v97, v10
	v_add_u32_e32 v11, 0xfffffa00, v10
	s_andn2_saveexec_b64 vcc, vcc
	v_add_u32_e32 v81, 0, v30
	v_fmac_f32_e32 v28, v10, v10
	v_add_u32_e32 v11, 0x100, v31
	v_add_u32_e32 v81, 0x1e800, v81
	ds_write_b32 v81, v10
	s_or_b64 exec, exec, vcc
	v_lshl_add_u32 v10, v11, 2, 0
	v_add_u32_e32 v11, 0x1fff8, v10
	ds_write_b32 v11, v9
	v_add_u32_e32 v11, 0x1fff0, v10
	v_add_u32_e32 v10, 0x1ffe8, v10
	ds_write_b32 v10, v8
	v_pk_mul_f32 v[8:9], v[8:9], v[8:9]
	ds_write_b32 v11, v80
	v_fma_f32 v9, v80, v80, v9
	v_add_f32_e32 v8, v8, v9
	v_add_f32_e32 v28, v8, v28

; __device__ __forceinline__ void phase_hyena(KP kp_, int hf){ asm volatile("" : "+s"(kp_)); const Params p=load_params(kp_);
;     ...
;       _Pragma("unroll 8") for (int i=0;i<64;++i){ int tl=wid+8*i;
;         const _Float16* ap=a3+(size_t)(tl*16+n)*64+kg*8;
;         f16x8 a0=*(const f16x8*)ap, a1=*(const f16x8*)(ap+32);
;         f32x4 dd={0.f,0.f,0.f,0.f};
;         dd=__builtin_amdgcn_mfma_f32_16x16x32_f16(a0,bw0,dd,0,0,0);
;         dd=__builtin_amdgcn_mfma_f32_16x16x32_f16(a1,bw1,dd,0,0,0);
;         if (n<4){ float d0=__expf(dsc*(float)(tl*16)); int lag0=tl*16+kg*4;
;           float v0=dd[0]*d0*pj0, v1=dd[1]*d0*pj1, v2=dd[2]*d0*pj2, v3=dd[3]*d0*pj3;
;           if (!side1){ Zf[2*(lag0)+order]=v0; Zf[2*(lag0+1)+order]=v1; Zf[2*(lag0+2)+order]=v2; Zf[2*(lag0+3)+order]=v3; ssl+=v0*v0+v1*v1+v2*v2+v3*v3; }
;           else { if (lag0>=1){ Zf[2*(16384-lag0)+order]=v0; ssl+=v0*v0; }
;             Zf[2*(16384-lag0-1)+order]=v1; Zf[2*(16384-lag0-2)+order]=v2; Zf[2*(16384-lag0-3)+order]=v3; ssl+=v1*v1+v2*v2+v3*v3; } }
.LBB0_1305:
	s_or_b64 exec, exec, s[50:51]
	s_nop 4
	s_nop 1
	s_nop 0
	s_waitcnt vmcnt(4)
	v_mfma_f32_16x16x32_f16 v[8:11], v[236:239], v[0:3], 0
	v_mfma_f32_16x16x32_f16 v[8:11], v[240:243], v[4:7], v[8:11]
	v_lshl_add_u64 v[84:85], v[12:13], 0, v[132:133]
	v_lshl_add_u64 v[84:85], v[84:85], 0, s[0:1]
	v_add_co_u32_e32 v84, vcc, 0x3b89000, v84
	s_nop 1
	v_addc_co_u32_e32 v85, vcc, 0, v85, vcc
	global_load_dwordx4 v[236:239], v[84:85], off
	global_load_dwordx4 v[240:243], v[84:85], off offset:64
	s_and_saveexec_b64 s[50:51], s[38:39]
	s_cbranch_execz .LBB0_1234
	v_add_u32_e32 v79, 0x380, v79
	v_cvt_f32_i32_e32 v79, v79
	v_mul_f32_e32 v79, v93, v79
	v_mul_f32_e32 v79, 0x3fb8aa3b, v79
	v_exp_f32_e32 v80, v79
	s_nop 0
	v_mul_f32_e32 v79, v8, v80
	v_mul_f32_e32 v81, v10, v80
	v_mov_b32_e32 v8, v11
	v_pk_mul_f32 v[8:9], v[8:9], v[80:81] op_sel_hi:[1,0]
	v_mul_f32_e32 v10, v95, v79
	v_mul_f32_e32 v79, v96, v81
	v_pk_mul_f32 v[8:9], v[50:51], v[8:9]
	s_and_saveexec_b64 s[12:13], s[40:41]
	s_xor_b64 s[12:13], exec, s[12:13]
	s_cbranch_execz .LBB0_1312
	v_add_u32_e32 v11, s18, v215
	v_add_u32_e32 v11, 0x380, v11
	v_cmp_gt_i32_e32 vcc, 1, v11
	s_and_saveexec_b64 s[26:27], vcc
	s_xor_b64 vcc, exec, s[26:27]
	v_add_u32_e32 v10, s22, v98
	v_add_lshl_u32 v10, v10, v94, 1
	v_sub_u32_e32 v10, v97, v10
	v_add_u32_e32 v11, 0xfffff900, v10
	s_andn2_saveexec_b64 vcc, vcc
	v_add_u32_e32 v11, 0, v30
	v_add_u32_e32 v11, 0x1e400, v11
	v_fmac_f32_e32 v28, v10, v10
	ds_write_b32 v11, v10
	v_mov_b32_e32 v11, v31
	s_or_b64 exec, exec, vcc
	v_lshl_add_u32 v10, v11, 2, 0
	v_add_u32_e32 v11, 0x1fff8, v10
	ds_write_b32 v11, v9
	v_add_u32_e32 v11, 0x1fff0, v10
	v_add_u32_e32 v10, 0x1ffe8, v10
	ds_write_b32 v10, v8
	v_pk_mul_f32 v[8:9], v[8:9], v[8:9]
	ds_write_b32 v11, v79
	v_fma_f32 v9, v79, v79, v9
	v_add_f32_e32 v8, v8, v9
	v_add_f32_e32 v28, v8, v28

; __device__ __forceinline__ void phase_hyena(KP kp_, int hf){ asm volatile("" : "+s"(kp_)); const Params p=load_params(kp_);
;     ...
;       }
;       ss0=(n<4 && order==0)?ssl:0.f; ss1=(n<4 && order==1)?ssl:0.f;
;     }
;     if (tid==0) Z[8192]=make_float2(0.f,0.f);
.LBB0_1314:
	s_waitcnt vmcnt(0)
	s_and_saveexec_b64 s[12:13], s[46:47]
	s_cbranch_execz .LBB0_1316
	v_readlane_b32 s18, v253, 23
	s_nop 1
	v_mov_b32_e32 v0, s18
	ds_write_b64 v0, v[220:221]
